# P12: each second-pass strip item shared by two workgroups (4 waves each), cross-workgroup halo hand-off by a flag word
# speedup vs baseline: 1.0121x; 1.0108x over previous
; #define MK_TID() ({ int w_ = wid0, z_ = 0; asm volatile("" : "+s"(w_), "+s"(z_)); w_ * 64 + (int)__builtin_amdgcn_mbcnt_hi(~0u, __builtin_amdgcn_mbcnt_lo(~0u, (unsigned)z_)); })
; __global__ void __launch_bounds__(512, 2) mk_fwd(Args a_) {
;     ...
;         unsigned char* ws = a->ws; unsigned char* ob = (unsigned char*)a->out;
;         float* ssq_qa = (float*)(ws + WS_SSQ_QA); float* ssq_kv = (float*)(ws + WS_SSQ_KV); float* ssq_x1 = (float*)(ws + WS_SSQ_X1); float* ssq_x2 = (float*)(ws + WS_SSQ_X2);
;         float* ropec = (float*)(ws + WS_ROPE); float* ropes = ropec + (size_t)MT * 32;
;         bf16_t* z1 = (bf16_t*)(ws + WS_Z1); bf16_t* ub = (bf16_t*)(ws + WS_U); bf16_t* z2a = (bf16_t*)(ws + WS_Z2A); bf16_t* z2b = (bf16_t*)(ob + O_Z2B);
;         bf16_t* qn = (bf16_t*)(ob + O_QN); bf16_t* qpe = (bf16_t*)(ob + O_QPE); bf16_t* kn = (bf16_t*)(ws + WS_KN); bf16_t* vb = (bf16_t*)(ws + WS_V); bf16_t* kpe = (bf16_t*)(ws + WS_KPE);
;         bf16_t* ya = (bf16_t*)(ws + WS_YA); bf16_t* ta = (bf16_t*)(ws + WS_TA); bf16_t* x1b = (bf16_t*)(ws + WS_X1B); bf16_t* x2b = (bf16_t*)(ws + WS_X2B);
;         bf16_t* memn = (bf16_t*)(ws + WS_MEMN); bf16_t* qc = (bf16_t*)(ws + WS_QC); bf16_t* kc = (bf16_t*)(ws + WS_KC); bf16_t* vc = (bf16_t*)(ws + WS_VC); bf16_t* oc = (bf16_t*)(ws + WS_OC);
;         bf16_t* h1 = (bf16_t*)(ws + WS_H1); bf16_t* h2 = (bf16_t*)(ws + WS_H2);
;     ...
;         } else if (ph == 12) {
;             const int tid = MK_TID();
;             for (int ui = bid; ui < 4 * 88; ui += G) { ffn_conv_item(tid, ui / 88, ui % 88, h1, h2, a->in[29], a->in[30], MK_DUPS != 12 || rep == 1); __syncthreads(); }
.LBB0_11:
	v_readlane_b32 s0, v252, 1
	v_readlane_b32 s4, v252, 0
	v_readlane_b32 s1, v252, 2
	s_mov_b32 s34, s4
	s_load_dwordx4 s[64:67], s[0:1], 0x100
	v_writelane_b32 v254, s20, 1
	s_mov_b32 s91, s22
	s_waitcnt lgkmcnt(0)
	s_add_u32 s4, s66, 0x6000000
	v_writelane_b32 v254, s21, 2
	v_writelane_b32 v254, s22, 3
	v_writelane_b32 v254, s23, 4
	s_addc_u32 s5, s67, 0
	v_writelane_b32 v254, s4, 5
	s_nop 1
	v_writelane_b32 v254, s5, 6
	s_add_u32 s4, s66, 0x10800000
	s_addc_u32 s5, s67, 0
	v_writelane_b32 v254, s4, 7
	s_nop 1
	v_writelane_b32 v254, s5, 8
	s_add_u32 s4, s66, 0x18800000
	s_addc_u32 s5, s67, 0
	v_writelane_b32 v254, s4, 9
	s_nop 1
	v_writelane_b32 v254, s5, 10
	s_add_u32 s4, s66, 0x11800000
	s_addc_u32 s5, s67, 0
	v_writelane_b32 v254, s4, 11
	s_nop 1
	v_writelane_b32 v254, s5, 12
	s_add_u32 s4, s66, 0x4a00000
	s_addc_u32 s5, s67, 0
	v_writelane_b32 v254, s4, 13
	s_cmp_lt_i32 s34, 32
	s_nop 0
	v_writelane_b32 v254, s5, 14
	s_cselect_b64 s[4:5], -1, 0
	s_add_u32 s10, s66, 0x1de80000
	v_writelane_b32 v254, s4, 15
	s_addc_u32 s11, s67, 0
	s_nop 0
	v_writelane_b32 v254, s5, 16
	s_add_u32 s4, s66, 0x1df10000
	s_addc_u32 s5, s67, 0
	s_add_u32 s6, s66, 0x1dc80000
	s_addc_u32 s7, s67, 0
	v_writelane_b32 v254, s6, 17
	s_nop 1
	v_writelane_b32 v254, s7, 18
	s_add_u32 s6, s66, 0x1df00000
	v_writelane_b32 v254, s6, 19
	s_addc_u32 s6, s67, 0
	v_writelane_b32 v254, s6, 20
	s_add_u32 s6, s66, 0x1cc00000
	s_addc_u32 s7, s67, 0
	s_and_b32 s8, s34, 7
	s_ashr_i32 s35, s34, 31
	v_writelane_b32 v254, s8, 21
	s_add_u32 s8, s66, 0x1de00000
	s_addc_u32 s9, s67, 0
	v_writelane_b32 v254, s8, 22
	s_nop 1
	v_writelane_b32 v254, s9, 23
	s_add_u32 s8, s66, 0x1dd00000
	s_addc_u32 s9, s67, 0
	v_writelane_b32 v254, s8, 24
	s_nop 1
	v_writelane_b32 v254, s9, 25
	s_add_u32 s8, s66, 0x1dd80000
	s_addc_u32 s9, s67, 0
	v_writelane_b32 v254, s8, 26
	s_nop 1
	v_writelane_b32 v254, s9, 27
	s_add_u32 s8, s66, 0x1dc00000
	s_addc_u32 s9, s67, 0
	v_writelane_b32 v254, s8, 28
	s_nop 1
	v_writelane_b32 v254, s9, 29
	s_add_u32 s8, s66, 0x800000
	s_addc_u32 s9, s67, 0
	v_writelane_b32 v254, s8, 30
	s_cmp_eq_u32 s22, 8
	s_nop 0
	v_writelane_b32 v254, s9, 31
	s_cselect_b64 s[8:9], -1, 0
	v_writelane_b32 v254, s8, 32
	s_cmp_lt_i32 s22, 5
	s_nop 0
	v_writelane_b32 v254, s9, 33
	v_writelane_b32 v254, s34, 34
	s_nop 1
	v_writelane_b32 v254, s35, 35
	s_cbranch_scc1 .LBB0_27
	s_cmp_gt_i32 s91, 10
	s_cbranch_scc0 .LBB0_29
	s_mov_b64 s[14:15], 0
	s_cmp_gt_i32 s91, 11
	s_mov_b64 s[12:13], 0
	s_mov_b64 s[16:17], 0
	s_cbranch_scc0 .LBB0_30
	s_cmp_eq_u32 s91, 12
	s_cbranch_scc0 .LBB0_68
	s_cmpk_gt_i32 s34, 0x15f
	s_mov_b32 s9, s39
	s_mov_b32 s8, s58
	s_cbranch_scc1 .LBB0_69
	s_load_dwordx4 s[44:47], s[0:1], 0xe8
	s_add_u32 s12, s66, 0xfa00000
	s_addc_u32 s13, s67, 0
	v_mbcnt_lo_u32_b32 v0, -1, s9
	v_mbcnt_hi_u32_b32 v0, -1, v0
	s_waitcnt lgkmcnt(0)
	s_add_u32 s16, s44, 0x5800
	s_addc_u32 s17, s45, 0
	s_add_u32 s20, s44, 0xb000
	s_addc_u32 s21, s45, 0
	s_add_u32 s22, s44, 0x10800
	s_addc_u32 s23, s45, 0
	s_add_u32 s24, s44, 0x16000
	s_addc_u32 s25, s45, 0
	s_add_u32 s28, s44, 0x1b800
	s_addc_u32 s29, s45, 0
	s_add_u32 s30, s46, 0x5800
	v_lshl_add_u32 v146, s8, 6, v0
	s_addc_u32 s31, s47, 0
	v_readlane_b32 s8, v254, 34
	v_readlane_b32 s9, v254, 35
	s_mov_b32 s18, 0
	v_writelane_b32 v255, s18, 46
	s_branch .LBB0_18
.LBB0_17:
	s_barrier
	v_readlane_b32 s18, v255, 46
	s_nop 3
	s_cmp_lg_u32 s18, 0
	s_cbranch_scc1 .LBB0_69
	s_cmpk_lt_i32 s56, 0x100
	s_cbranch_scc1 .Lc2_plain
	v_readlane_b32 s8, v254, 34
	s_nop 3
	s_cmpk_gt_i32 s8, 0xbf
	s_cbranch_scc1 .LBB0_69
	s_cmpk_lt_i32 s8, 0x60
	s_cselect_b32 s18, 1, 3
	s_movk_i32 s9, 0xa0
	s_cselect_b32 s9, 0x100, s9
	s_add_i32 s8, s8, s9
	v_writelane_b32 v255, s18, 46
	s_branch .LBB0_18
.Lc2_plain:
	s_add_i32 s8, s8, s56
	s_cmpk_lt_i32 s8, 0x160
	s_cbranch_scc0 .LBB0_69
.LBB0_18:
	v_readlane_b32 s9, v255, 46
	s_nop 3
	s_cmp_eq_u32 s9, 0
	s_cbranch_scc1 .Lc2_go
	s_lshr_b32 s9, s9, 1
	s_lshr_b32 s18, s58, 2
	s_cmp_eq_u32 s9, s18
	s_cbranch_scc1 .Lc2_go
	s_barrier
	s_branch .LBB0_17

; __device__ __forceinline__ void ffn_conv_item(int tid_in, int b, int strip, bf16_t* h1, const bf16_t* h2, const float* cw, const float* cb, bool st = true) {
;     ...
;     const size_t off0 = ((size_t)b * SEQL + 512 * wid) * 5632 + ch;
;     u32x4 pg = {0u, 0u, 0u, 0u}, pv = {0u, 0u, 0u, 0u};
;     if (wid > 0) { pg = *(const u32x4*)(h1 + off0 + (ptrdiff_t)(rl - 8) * 5632); pv = *(const u32x4*)(h2 + off0 + (ptrdiff_t)(rl - 8) * 5632); }
;     asm volatile("s_waitcnt vmcnt(0)" ::: "memory");
;     __syncthreads();
;     u32x4 cg4[4], cv4[4];
; #pragma unroll
;     for (int j = 0; j < 4; ++j) { cg4[j] = __builtin_nontemporal_load((const u32x4*)(h1 + off0 + (size_t)(8 * j + rl) * 5632)); cv4[j] = __builtin_nontemporal_load((const u32x4*)(h2 + off0 + (size_t)(8 * j + rl) * 5632)); }
.LBB0_23:
	v_lshlrev_b64 v[70:71], 1, v[0:1]
	v_lshl_add_u64 v[36:37], v[36:37], 0, v[70:71]
	v_lshl_add_u64 v[34:35], v[34:35], 0, v[70:71]
	v_add_co_u32_e32 v70, vcc, 0x16000, v36
	s_waitcnt vmcnt(0)
	s_nop 1
	v_addc_co_u32_e32 v71, vcc, 0, v37, vcc
	v_add_co_u32_e32 v72, vcc, 0x16000, v34
	s_barrier
	s_nop 0
	v_addc_co_u32_e32 v73, vcc, 0, v35, vcc
	v_readlane_b32 s18, v255, 46
	s_nop 3
	s_cmp_eq_u32 s18, 3
	s_cbranch_scc0 .Lc2_notb
	s_cmp_eq_u32 s58, 4
	s_cbranch_scc0 .Lc2_done
	v_mov_b32_e32 v200, s8
	v_mov_b32_e32 v201, 1
	v_lshlrev_b32_e32 v200, 2, v200
	v_add_u32_e32 v200, 0x6032b0, v200
	s_mov_b64 s[18:19], exec
	s_mov_b64 exec, 1
	global_atomic_add v200, v201, s[66:67]
	s_mov_b64 exec, s[18:19]
	s_branch .Lc2_done
.Lc2_notb:
	s_cmp_eq_u32 s18, 1
	s_cbranch_scc0 .Lc2_done
	s_cmp_eq_u32 s58, 3
	s_cbranch_scc0 .Lc2_done
	v_mov_b32_e32 v200, s8
	s_mov_b32 s18, 0
	v_lshlrev_b32_e32 v200, 2, v200
	v_add_u32_e32 v200, 0x6032b0, v200
.Lc2_spin:
	global_load_dword v201, v200, s[66:67] sc1
	s_waitcnt vmcnt(0)
	v_readfirstlane_b32 s19, v201
	s_nop 3
	s_cmp_lg_u32 s19, 0
	s_cbranch_scc1 .Lc2_done
	s_sleep 2
	s_add_i32 s18, s18, 1
	s_cmp_lt_u32 s18, 0x40000
	s_cbranch_scc1 .Lc2_spin
.Lc2_done:
	global_load_dwordx4 v[94:97], v[36:37], off nt
	global_load_dwordx4 v[98:101], v[34:35], off nt
	global_load_dwordx4 v[82:85], v[70:71], off nt
	global_load_dwordx4 v[86:89], v[72:73], off nt
	v_add_co_u32_e32 v70, vcc, 0x2c000, v36
	v_and_b32_e32 v107, 64, v220
	s_nop 0
	v_addc_co_u32_e32 v71, vcc, 0, v37, vcc
	v_add_co_u32_e32 v72, vcc, 0x2c000, v34
	v_add_u32_e32 v0, 56, v106
	s_nop 0
	v_addc_co_u32_e32 v73, vcc, 0, v35, vcc
	v_add_co_u32_e32 v36, vcc, 0x42000, v36
	global_load_dwordx4 v[74:77], v[70:71], off nt
	global_load_dwordx4 v[78:81], v[72:73], off nt
	v_addc_co_u32_e32 v37, vcc, 0, v37, vcc
	v_add_co_u32_e32 v70, vcc, 0x42000, v34
	v_add_u32_e32 v106, 48, v106
	s_nop 0
	v_addc_co_u32_e32 v71, vcc, 0, v35, vcc
	global_load_dwordx4 v[34:37], v[36:37], off nt
	s_nop 0
	global_load_dwordx4 v[70:73], v[70:71], off nt
	s_movk_i32 s9, 0x2c00
	v_and_or_b32 v0, v0, 63, v107
	v_and_or_b32 v106, v106, 63, v107
	s_waitcnt vmcnt(20)
	v_mov_b32_e32 v136, v38
	v_mov_b32_e32 v137, v6
	v_mov_b32_e32 v6, v39
	v_mad_u64_u32 v[38:39], s[18:19], v140, s9, v[138:139]
	v_cmp_eq_u32_e64 s[40:41], 7, v140
	v_lshlrev_b32_e32 v0, 2, v0
	v_cmp_gt_u32_e64 s[42:43], 6, v140
	v_lshlrev_b32_e32 v147, 2, v106
	s_waitcnt vmcnt(9)
	v_mov_b32_e32 v106, v68
	v_mov_b32_e32 v107, v28
	v_mov_b32_e32 v108, v64
	v_mov_b32_e32 v109, v20
	v_mov_b32_e32 v110, v60
	v_mov_b32_e32 v111, v12
	v_mov_b32_e32 v112, v56
	v_mov_b32_e32 v113, v4
	v_mov_b32_e32 v28, v69
	v_mov_b32_e32 v20, v65
	v_mov_b32_e32 v12, v61
	v_mov_b32_e32 v4, v57
	v_mov_b32_e32 v114, v66
	v_mov_b32_e32 v115, v26
	v_mov_b32_e32 v116, v62
	v_mov_b32_e32 v117, v18
	v_mov_b32_e32 v118, v58
	v_mov_b32_e32 v119, v10
	v_mov_b32_e32 v120, v54
	v_mov_b32_e32 v121, v2
	v_mov_b32_e32 v26, v67
	v_mov_b32_e32 v18, v63
	v_mov_b32_e32 v10, v59
	v_mov_b32_e32 v2, v55
	s_waitcnt vmcnt(8)
	v_mov_b32_e32 v122, v52
	v_mov_b32_e32 v123, v32
	v_mov_b32_e32 v124, v48
	v_mov_b32_e32 v125, v24
	v_mov_b32_e32 v126, v44
	v_mov_b32_e32 v127, v16
	v_mov_b32_e32 v128, v40
	v_mov_b32_e32 v129, v8
	v_mov_b32_e32 v32, v53
	v_mov_b32_e32 v24, v49
	v_mov_b32_e32 v16, v45
	v_mov_b32_e32 v8, v41
	v_mov_b32_e32 v130, v50
	v_mov_b32_e32 v131, v30
	v_mov_b32_e32 v132, v46
	v_mov_b32_e32 v133, v22
	v_mov_b32_e32 v134, v42
	v_mov_b32_e32 v135, v14
	v_mov_b32_e32 v30, v51
	v_mov_b32_e32 v22, v47
	v_mov_b32_e32 v14, v43
	v_lshl_add_u64 v[138:139], s[66:67], 0, v[38:39]
	s_mov_b64 s[34:35], 0
	s_branch .LBB0_25

; __device__ __forceinline__ void ffn_conv_item(int tid_in, int b, int strip, bf16_t* h1, const bf16_t* h2, const float* cw, const float* cb, bool st = true) {
;     ...
; #pragma nounroll
;     for (int blk = 0; blk < 16; ++blk) {
;         u32x4 ng4[4], nv4[4];
;         if (blk + 1 < 16) {
; #pragma unroll
;             for (int j = 0; j < 4; ++j) { const size_t o_ = off0 + (size_t)(32 * (blk + 1) + 8 * j + rl) * 5632; ng4[j] = __builtin_nontemporal_load((const u32x4*)(h1 + o_)); nv4[j] = __builtin_nontemporal_load((const u32x4*)(h2 + o_)); }
;         }
.LBB0_25:
	s_waitcnt vmcnt(1)
	v_mov_b64_e32 v[48:49], v[36:37]
	v_mov_b64_e32 v[46:47], v[34:35]
	s_cmp_eq_u32 s34, 0x528000
	v_lshl_add_u64 v[140:141], v[138:139], 0, s[34:35]
	s_cbranch_scc1 .LBB0_24
	v_add_co_u32_e32 v34, vcc, 0x4a58000, v140
	s_nop 1
	v_addc_co_u32_e32 v35, vcc, 0, v141, vcc
	v_add_co_u32_e32 v36, vcc, 0xfa58000, v140
	s_nop 1
	v_addc_co_u32_e32 v37, vcc, 0, v141, vcc
	global_load_dwordx4 v[38:41], v[34:35], off nt
	global_load_dwordx4 v[42:45], v[36:37], off nt
	v_add_co_u32_e32 v34, vcc, 0x4a6e000, v140
	s_nop 1
	v_addc_co_u32_e32 v35, vcc, 0, v141, vcc
	v_add_co_u32_e32 v36, vcc, 0xfa6e000, v140
	s_nop 1
	v_addc_co_u32_e32 v37, vcc, 0, v141, vcc
	global_load_dwordx4 v[50:53], v[34:35], off nt
	global_load_dwordx4 v[54:57], v[36:37], off nt
	v_add_co_u32_e32 v34, vcc, 0x4a84000, v140
	s_nop 1
	v_addc_co_u32_e32 v35, vcc, 0, v141, vcc
	v_add_co_u32_e32 v36, vcc, 0xfa84000, v140
	s_nop 1
	v_addc_co_u32_e32 v37, vcc, 0, v141, vcc
	global_load_dwordx4 v[58:61], v[34:35], off nt
	global_load_dwordx4 v[62:65], v[36:37], off nt
	v_add_co_u32_e32 v34, vcc, 0x4a9a000, v140
	s_nop 1
	v_addc_co_u32_e32 v35, vcc, 0, v141, vcc
	v_add_co_u32_e32 v66, vcc, 0xfa9a000, v140
	s_nop 1
	v_addc_co_u32_e32 v67, vcc, 0, v141, vcc
	global_load_dwordx4 v[34:37], v[34:35], off nt
	s_nop 0
	global_load_dwordx4 v[66:69], v[66:67], off nt
	s_branch .LBB0_24
	s_nop 0
	s_nop 0
	s_nop 0
	s_nop 0
	s_nop 0
	s_nop 0
	s_nop 0
	s_nop 0
	s_nop 0
	s_nop 0
	s_nop 0
	s_nop 0
	s_nop 0
	s_nop 0
	s_nop 0
	s_nop 0
	s_nop 0
	s_nop 0
	s_nop 0
	s_nop 0
	s_nop 0
	s_nop 0
	s_nop 0
	s_nop 0
	s_nop 0
	s_nop 0
	s_nop 0
	s_nop 0
	s_nop 0
	s_nop 0
	s_nop 0
	s_nop 0
	s_nop 0
	s_nop 0
	s_nop 0
	s_nop 0
	s_nop 0
	s_nop 0
	s_nop 0
	s_nop 0
	s_nop 0
	s_nop 0
	s_nop 0
	s_nop 0
	s_nop 0
	s_nop 0
	s_nop 0
	s_nop 0
	s_nop 0
	s_nop 0
	s_nop 0
	s_nop 0
	s_nop 0
	s_nop 0
	s_nop 0
	s_nop 0
	s_nop 0
	s_nop 0
	s_nop 0
	s_nop 0
	s_nop 0
	s_nop 0
	s_nop 0
	s_nop 0
	s_nop 0
	s_nop 0
	s_nop 0
	s_nop 0
	s_nop 0
	s_nop 0
	s_nop 0
	s_nop 0
	s_nop 0
	s_nop 0
	s_nop 0
	s_nop 0
	s_nop 0
	s_nop 0
	s_nop 0
	s_nop 0
	s_nop 0
	s_nop 0
	s_nop 0
	s_nop 0
	s_nop 0
	s_nop 0
	s_nop 0
	s_nop 0
	s_nop 0
	s_nop 0
	s_nop 0
	s_nop 0
	s_nop 0
	s_nop 0
	s_nop 0
	s_nop 0
	s_nop 0
	s_nop 0
	s_nop 0
	s_nop 0
	s_nop 0
	s_nop 0
	s_nop 0
	s_nop 0
	s_nop 0
	s_nop 0
	s_nop 0
	s_nop 0
	s_nop 0
	s_nop 0
	s_nop 0
	s_nop 0
	s_nop 0
	s_nop 0
	s_nop 0
	s_nop 0
	s_nop 0
	s_nop 0
	s_nop 0
	s_nop 0
	s_nop 0
	s_nop 0
	s_nop 0
	s_nop 0
	s_nop 0
	s_nop 0
	s_nop 0
	s_nop 0
	s_nop 0
	s_nop 0
	s_nop 0
	s_nop 0
	s_nop 0
	s_nop 0
	s_nop 0
	s_nop 0
	s_nop 0
	s_nop 0
	s_nop 0
	s_nop 0
	s_nop 0
	s_nop 0
	s_nop 0
	s_nop 0
	s_nop 0
	s_nop 0
	s_nop 0
	s_nop 0
	s_nop 0
	s_nop 0
	s_nop 0
	s_nop 0
	s_nop 0
	s_nop 0
	s_nop 0
	s_nop 0
	s_nop 0
	s_nop 0
	s_nop 0
	s_nop 0
	s_nop 0
	s_nop 0
	s_nop 0
	s_nop 0
	s_nop 0
	s_nop 0
	s_nop 0
	s_nop 0
	s_nop 0
	s_nop 0
	s_nop 0
	s_nop 0
	s_nop 0
	s_nop 0
	s_nop 0
	s_nop 0
	s_nop 0
	s_nop 0
	s_nop 0
	s_nop 0
	s_nop 0
	s_nop 0
	s_nop 0
	s_nop 0
	s_nop 0
	s_nop 0
	s_nop 0
	s_nop 0
	s_nop 0
	s_nop 0
	s_nop 0
	s_nop 0
	s_nop 0
	s_nop 0
	s_nop 0
	s_nop 0
	s_nop 0
	s_nop 0
	s_nop 0
	s_nop 0
	s_nop 0
	s_nop 0
	s_nop 0
	s_nop 0
	s_nop 0
	s_nop 0
	s_nop 0
	s_nop 0
	s_nop 0
	s_nop 0
	s_nop 0
	s_nop 0
	s_nop 0
	s_nop 0
	s_nop 0
	s_nop 0
	s_nop 0
	s_nop 0
	s_nop 0
	s_nop 0
	s_nop 0
	s_nop 0
	s_nop 0
	s_nop 0
	s_nop 0
	s_nop 0
	s_nop 0
	s_nop 0
	s_nop 0
	s_nop 0
	s_nop 0
	s_nop 0
	s_nop 0
	s_nop 0
	s_nop 0
	s_nop 0
	s_nop 0
	s_nop 0
	s_nop 0
	s_nop 0
	s_nop 0
	s_nop 0
	s_nop 0
	s_nop 0
	s_nop 0
	s_nop 0
	s_nop 0
	s_nop 0
	s_nop 0
	s_nop 0
	s_nop 0
	s_nop 0
	s_nop 0
	s_nop 0
	s_nop 0
	s_nop 0
	s_nop 0
	s_nop 0
	s_nop 0
	s_nop 0
	s_nop 0
	s_nop 0
	s_nop 0
	s_nop 0
	s_nop 0
	s_nop 0
	s_nop 0
	s_nop 0
	s_nop 0
	s_nop 0
	s_nop 0
	s_nop 0
	s_nop 0
	s_nop 0
	s_nop 0
	s_nop 0
	s_nop 0
	s_nop 0
	s_nop 0
	s_nop 0
	s_nop 0
	s_nop 0
	s_nop 0
	s_nop 0
	s_nop 0
	s_nop 0
	s_nop 0
	s_nop 0
	s_nop 0
	s_nop 0
	s_nop 0
	s_nop 0
	s_nop 0
	s_nop 0
	s_nop 0
	s_nop 0
	s_nop 0
	s_nop 0
	s_nop 0
	s_nop 0
	s_nop 0
	s_nop 0
	s_nop 0
	s_nop 0
	s_nop 0
	s_nop 0
	s_nop 0
	s_nop 0
	s_nop 0
	s_nop 0
	s_nop 0
	s_nop 0
	s_nop 0
	s_nop 0
	s_nop 0
	s_nop 0
	s_nop 0
	s_nop 0
	s_nop 0
	s_nop 0
	s_nop 0
	s_nop 0
	s_nop 0
	s_nop 0
	s_nop 0
	s_nop 0
	s_nop 0
	s_nop 0
	s_nop 0
	s_nop 0
	s_nop 0
	s_nop 0
	s_nop 0
	s_nop 0
	s_nop 0
	s_nop 0
	s_nop 0
	s_nop 0
	s_nop 0
	s_nop 0
	s_nop 0
	s_nop 0
	s_nop 0
	s_nop 0
	s_nop 0
	s_nop 0
	s_nop 0
	s_nop 0
	s_nop 0
	s_nop 0
	s_nop 0
	s_nop 0
	s_nop 0
	s_nop 0
	s_nop 0
	s_nop 0
	s_nop 0
	s_nop 0
	s_nop 0
	s_nop 0
	s_nop 0
	s_nop 0
	s_nop 0
	s_nop 0
	s_nop 0
	s_nop 0
	s_nop 0
	s_nop 0
	s_nop 0
	s_nop 0
	s_nop 0
	s_nop 0
	s_nop 0
	s_nop 0
	s_nop 0
	s_nop 0
	s_nop 0
	s_nop 0
	s_nop 0
	s_nop 0
	s_nop 0
	s_nop 0
	s_nop 0
	s_nop 0
	s_nop 0
	s_nop 0
	s_nop 0
	s_nop 0
	s_nop 0
	s_nop 0
	s_nop 0
	s_nop 0
	s_nop 0
	s_nop 0
	s_nop 0
	s_nop 0
	s_nop 0
	s_nop 0
	s_nop 0
	s_nop 0
	s_nop 0
	s_nop 0
	s_nop 0
	s_nop 0
	s_nop 0
	s_nop 0
	s_nop 0
	s_nop 0
	s_nop 0
	s_nop 0
	s_nop 0
	s_nop 0
	s_nop 0
	s_nop 0
	s_nop 0
	s_nop 0
	s_nop 0
	s_nop 0
	s_nop 0
	s_nop 0
	s_nop 0
	s_nop 0
	s_nop 0
	s_nop 0
	s_nop 0
	s_nop 0
	s_nop 0
	s_nop 0
	s_nop 0
	s_nop 0
	s_nop 0
	s_nop 0
	s_nop 0
	s_nop 0
	s_nop 0
	s_nop 0
	s_nop 0
.LBB0_27:
	s_mov_b64 s[12:13], 0
	s_mov_b64 s[16:17], 0
	s_cbranch_execnz .LBB0_95
